# final_norm: g vectors hoisted out of loop, cross-trip row prefetch (counted vmcnt(8) leaves nt stores in flight)
# baseline (speedup 1.0000x reference)
.LBB0_2640:
	v_lshrrev_b32_e32 v0, 6, v168
	v_lshl_add_u32 v32, s12, 3, v0
	s_mov_b32 s7, 0x8000
	v_cmp_gt_i32_e32 vcc, s7, v32
	s_and_saveexec_b64 s[0:1], vcc
	s_cbranch_execz .LBB0_2651
	v_mbcnt_lo_u32_b32 v0, -1, 0
	v_mbcnt_hi_u32_b32 v0, -1, v0
	v_and_b32_e32 v1, 64, v0
	v_add_u32_e32 v1, 64, v1
	v_xor_b32_e32 v2, 1, v0
	v_cmp_lt_i32_e32 vcc, v2, v1
	v_readlane_b32 s12, v244, 17
	v_readlane_b32 s26, v244, 31
	v_cndmask_b32_e32 v2, v0, v2, vcc
	v_lshlrev_b32_e32 v41, 2, v2
	v_xor_b32_e32 v2, 2, v0
	v_cmp_lt_i32_e32 vcc, v2, v1
	v_readlane_b32 s27, v244, 32
	s_lshl_b32 s8, s70, 3
	v_cndmask_b32_e32 v2, v0, v2, vcc
	v_lshlrev_b32_e32 v54, 2, v2
	v_xor_b32_e32 v2, 4, v0
	v_cmp_lt_i32_e32 vcc, v2, v1
	s_mov_b64 s[4:5], 0
	s_mov_b32 s6, 0x3a800000
	v_cndmask_b32_e32 v2, v0, v2, vcc
	v_lshlrev_b32_e32 v55, 2, v2
	v_xor_b32_e32 v2, 8, v0
	v_cmp_lt_i32_e32 vcc, v2, v1
	v_mov_b32_e32 v40, 0x358637bd
	s_mov_b32 s9, 0x800000
	v_cndmask_b32_e32 v2, v0, v2, vcc
	v_lshlrev_b32_e32 v56, 2, v2
	v_xor_b32_e32 v2, 16, v0
	v_cmp_lt_i32_e32 vcc, v2, v1
	s_movk_i32 s10, 0x7fff
	v_readlane_b32 s13, v244, 18
	v_cndmask_b32_e32 v2, v0, v2, vcc
	v_lshlrev_b32_e32 v57, 2, v2
	v_xor_b32_e32 v2, 32, v0
	v_cmp_lt_i32_e32 vcc, v2, v1
	v_mov_b32_e32 v1, 0
	v_readlane_b32 s14, v244, 19
	v_cndmask_b32_e32 v0, v0, v2, vcc
	v_lshlrev_b32_e32 v58, 2, v0
	v_lshlrev_b32_e32 v0, 4, v168
	v_and_b32_e32 v0, 0x3f0, v0
	v_lshl_add_u64 v[36:37], s[26:27], 0, v[0:1]
	v_lshl_add_u64 v[38:39], s[72:73], 0, v[0:1]
	v_readlane_b32 s15, v244, 20
	v_readlane_b32 s16, v244, 21
	v_readlane_b32 s17, v244, 22
	v_readlane_b32 s18, v244, 23
	v_readlane_b32 s19, v244, 24
	v_readlane_b32 s20, v244, 25
	v_readlane_b32 s21, v244, 26
	v_readlane_b32 s22, v244, 27
	v_readlane_b32 s23, v244, 28
	v_readlane_b32 s24, v244, 29
	v_readlane_b32 s25, v244, 30
	v_mov_b32_e32 v141, 0
	v_mov_b32_e32 v143, 0
	global_load_dwordx4 v[136:139], v[36:37], off
	global_load_dwordx4 v[84:87], v[36:37], off offset:1024
	global_load_dwordx4 v[88:91], v[36:37], off offset:1024
	global_load_dwordx4 v[92:95], v[36:37], off offset:2048
	global_load_dwordx4 v[96:99], v[36:37], off offset:3072
	global_load_dwordx4 v[100:103], v[36:37], off offset:3072
	v_mov_b32_e32 v140, v32
	v_add_u32_e32 v142, s8, v32
	v_lshlrev_b64 v[144:145], 12, v[140:141]
	v_cmp_gt_i32_e32 vcc, s7, v142
	v_lshl_add_u64 v[144:145], v[38:39], 0, v[144:145]
	s_nop 0
	v_cndmask_b32_e32 v142, v32, v142, vcc
	v_lshlrev_b64 v[146:147], 12, v[142:143]
	v_lshl_add_u64 v[146:147], v[38:39], 0, v[146:147]
	global_load_dwordx4 v[104:107], v[144:145], off nt
	global_load_dwordx4 v[108:111], v[144:145], off offset:1024 nt
	global_load_dwordx4 v[112:115], v[144:145], off offset:3072 nt
	global_load_dwordx4 v[116:119], v[144:145], off offset:2048 nt
	global_load_dwordx4 v[120:123], v[146:147], off nt
	global_load_dwordx4 v[124:127], v[146:147], off offset:1024 nt
	global_load_dwordx4 v[128:131], v[146:147], off offset:3072 nt
	global_load_dwordx4 v[132:135], v[146:147], off offset:2048 nt
	s_waitcnt vmcnt(0)
	s_branch .LBB0_2643

.LBB0_2643:
	v_ashrrev_i32_e32 v33, 31, v32
	v_lshlrev_b64 v[46:47], 12, v[32:33]
	v_add_u32_e32 v59, s8, v32
	v_lshl_add_u64 v[44:45], v[38:39], 0, v[46:47]
	v_cmp_gt_i32_e32 vcc, s7, v59
	v_add_u32_e32 v140, s8, v59
	s_nop 1
	v_cndmask_b32_e32 v34, v32, v59, vcc
	v_cmp_gt_i32_e32 vcc, s7, v140
	v_ashrrev_i32_e32 v35, 31, v34
	v_lshlrev_b64 v[42:43], 12, v[34:35]
	v_cndmask_b32_e32 v140, v32, v140, vcc
	v_lshl_add_u64 v[48:49], v[38:39], 0, v[42:43]
	v_add_u32_e32 v142, s8, v140
	v_lshlrev_b64 v[144:145], 12, v[140:141]
	v_cmp_gt_i32_e32 vcc, s7, v142
	v_lshl_add_u64 v[144:145], v[38:39], 0, v[144:145]
	s_nop 0
	v_cndmask_b32_e32 v142, v140, v142, vcc
	s_waitcnt vmcnt(8)
	v_mov_b64_e32 v[60:61], v[104:105]
	v_mov_b64_e32 v[62:63], v[106:107]
	v_mov_b64_e32 v[16:17], v[108:109]
	v_mov_b64_e32 v[18:19], v[110:111]
	v_mov_b64_e32 v[0:1], v[112:113]
	v_mov_b64_e32 v[2:3], v[114:115]
	v_mov_b64_e32 v[12:13], v[116:117]
	v_mov_b64_e32 v[14:15], v[118:119]
	v_mov_b64_e32 v[24:25], v[120:121]
	v_mov_b64_e32 v[26:27], v[122:123]
	v_mov_b64_e32 v[20:21], v[124:125]
	v_mov_b64_e32 v[22:23], v[126:127]
	v_mov_b64_e32 v[4:5], v[128:129]
	v_mov_b64_e32 v[6:7], v[130:131]
	v_mov_b64_e32 v[8:9], v[132:133]
	v_mov_b64_e32 v[10:11], v[134:135]
	v_mov_b64_e32 v[28:29], v[136:137]
	v_mov_b64_e32 v[30:31], v[138:139]
	v_lshlrev_b64 v[146:147], 12, v[142:143]
	v_lshl_add_u64 v[146:147], v[38:39], 0, v[146:147]
	global_load_dwordx4 v[104:107], v[144:145], off nt
	global_load_dwordx4 v[108:111], v[144:145], off offset:1024 nt
	global_load_dwordx4 v[112:115], v[144:145], off offset:3072 nt
	global_load_dwordx4 v[116:119], v[144:145], off offset:2048 nt
	global_load_dwordx4 v[120:123], v[146:147], off nt
	global_load_dwordx4 v[124:127], v[146:147], off offset:1024 nt
	global_load_dwordx4 v[128:131], v[146:147], off offset:3072 nt
	global_load_dwordx4 v[132:135], v[146:147], off offset:2048 nt
	v_cmp_ne_u32_e32 vcc, v32, v34
	v_pk_mul_f32 v[50:51], v[62:63], v[62:63]
	v_pk_mul_f32 v[52:53], v[60:61], v[60:61]
	v_pk_mul_f32 v[64:65], v[18:19], v[18:19]
	v_pk_mul_f32 v[66:67], v[16:17], v[16:17]
	v_mul_f32_e32 v68, v13, v13
	v_mul_f32_e32 v70, v15, v15
	v_pk_mov_b32 v[72:73], v[52:53], v[50:51] op_sel:[1,0]
	v_mov_b32_e32 v53, v51
	v_pk_mov_b32 v[50:51], v[66:67], v[64:65] op_sel:[1,0]
	v_mov_b32_e32 v67, v65
	v_pk_fma_f32 v[64:65], v[12:13], v[12:13], v[68:69] op_sel_hi:[1,1,0]
	v_pk_fma_f32 v[68:69], v[14:15], v[14:15], v[70:71] op_sel_hi:[1,1,0]
	v_pk_add_f32 v[52:53], v[72:73], v[52:53]
	v_pk_mul_f32 v[70:71], v[26:27], v[26:27]
	v_pk_mul_f32 v[72:73], v[24:25], v[24:25]
	v_pk_add_f32 v[50:51], v[50:51], v[66:67]
	v_pk_mul_f32 v[66:67], v[22:23], v[22:23]
	v_pk_mul_f32 v[74:75], v[20:21], v[20:21]
	v_mul_f32_e32 v33, v0, v0
	v_mul_f32_e32 v35, v1, v1
	v_mul_f32_e32 v76, v2, v2
	v_mul_f32_e32 v77, v3, v3
	v_pk_mov_b32 v[80:81], v[72:73], v[70:71] op_sel:[1,0]
	v_mov_b32_e32 v73, v71
	v_pk_mov_b32 v[70:71], v[74:75], v[66:67] op_sel:[1,0]
	v_mov_b32_e32 v75, v67
	v_pk_add_f32 v[52:53], v[52:53], v[52:53] op_sel:[0,1] op_sel_hi:[1,0]
	v_pk_add_f32 v[50:51], v[50:51], v[50:51] op_sel:[0,1] op_sel_hi:[1,0]
	v_mov_b32_e32 v65, v76
	v_mov_b32_e32 v69, v77
	v_mul_f32_e32 v77, v4, v4
	v_mul_f32_e32 v79, v5, v5
	v_mul_f32_e32 v76, v9, v9
	v_mul_f32_e32 v78, v11, v11
	v_pk_add_f32 v[72:73], v[80:81], v[72:73]
	v_pk_add_f32 v[70:71], v[70:71], v[74:75]
	v_mov_b32_e32 v53, v33
	v_mov_b32_e32 v51, v35
	v_mul_f32_e32 v82, v6, v6
	v_mul_f32_e32 v83, v7, v7
	v_pk_add_f32 v[64:65], v[64:65], v[68:69]
	v_pk_fma_f32 v[66:67], v[8:9], v[8:9], v[76:77] op_sel_hi:[1,1,0]
	v_pk_fma_f32 v[68:69], v[10:11], v[10:11], v[78:79] op_sel_hi:[1,1,0]
	v_pk_add_f32 v[50:51], v[52:53], v[50:51]
	v_pk_add_f32 v[52:53], v[72:73], v[72:73] op_sel:[0,1] op_sel_hi:[1,0]
	v_pk_add_f32 v[70:71], v[70:71], v[70:71] op_sel:[0,1] op_sel_hi:[1,0]
	v_mov_b32_e32 v67, v82
	v_mov_b32_e32 v69, v83
	v_mov_b32_e32 v53, v77
	v_mov_b32_e32 v71, v79
	v_pk_add_f32 v[66:67], v[66:67], v[68:69]
	v_pk_add_f32 v[52:53], v[52:53], v[70:71]
	v_pk_add_f32 v[50:51], v[50:51], v[64:65]
	v_pk_add_f32 v[52:53], v[52:53], v[66:67]
	v_mov_b32_e32 v65, v50
	v_mov_b32_e32 v64, v52
	v_mov_b32_e32 v50, v53
	v_pk_add_f32 v[50:51], v[64:65], v[50:51]
	ds_bpermute_b32 v53, v41, v51
	ds_bpermute_b32 v52, v41, v50
	s_waitcnt lgkmcnt(0)
	v_pk_add_f32 v[50:51], v[50:51], v[52:53]
	ds_bpermute_b32 v53, v54, v51
	ds_bpermute_b32 v52, v54, v50
	s_waitcnt lgkmcnt(0)
	v_pk_add_f32 v[50:51], v[50:51], v[52:53]
	ds_bpermute_b32 v53, v55, v51
	ds_bpermute_b32 v52, v55, v50
	s_waitcnt lgkmcnt(0)
	v_pk_add_f32 v[50:51], v[50:51], v[52:53]
	ds_bpermute_b32 v53, v56, v51
	ds_bpermute_b32 v52, v56, v50
	s_waitcnt lgkmcnt(0)
	v_pk_add_f32 v[50:51], v[50:51], v[52:53]
	ds_bpermute_b32 v53, v57, v51
	ds_bpermute_b32 v52, v57, v50
	s_waitcnt lgkmcnt(0)
	v_pk_add_f32 v[50:51], v[50:51], v[52:53]
	ds_bpermute_b32 v53, v58, v51
	ds_bpermute_b32 v52, v58, v50
	s_waitcnt lgkmcnt(0)
	s_nop 0
	v_pk_add_f32 v[50:51], v[50:51], v[52:53]
	s_nop 0
	v_pk_fma_f32 v[50:51], v[50:51], s[6:7], v[40:41] op_sel_hi:[1,0,0]
	s_nop 0
	v_mul_f32_e32 v33, 0x4b800000, v51
	v_cmp_gt_f32_e64 s[0:1], s9, v51
	v_mul_f32_e32 v35, 0x4b800000, v50
	v_cmp_gt_f32_e64 s[2:3], s9, v50
	v_cndmask_b32_e64 v33, v51, v33, s[0:1]
	v_rsq_f32_e32 v33, v33
	v_cndmask_b32_e64 v35, v50, v35, s[2:3]
	v_rsq_f32_e32 v35, v35
	v_mul_f32_e32 v32, 0x45800000, v33
	v_cndmask_b32_e64 v52, v33, v32, s[0:1]
	v_mul_f32_e32 v34, 0x45800000, v35
	v_mov_b32_e32 v53, v52
	v_cndmask_b32_e64 v50, v35, v34, s[2:3]
	v_pk_mul_f32 v[32:33], v[60:61], v[52:53] op_sel_hi:[1,0]
	v_pk_mul_f32 v[34:35], v[62:63], v[52:53] op_sel_hi:[1,0]
	v_mov_b32_e32 v51, v50
	v_pk_mul_f32 v[34:35], v[30:31], v[34:35]
	v_pk_mul_f32 v[32:33], v[28:29], v[32:33]
	v_pk_mul_f32 v[16:17], v[16:17], v[52:53]
	global_store_dwordx4 v[44:45], v[32:35], off nt
	s_and_saveexec_b64 s[0:1], vcc
	s_xor_b64 s[0:1], exec, s[0:1]
	s_cbranch_execz .LBB0_2645
	v_mov_b32_e32 v32, v50
	v_mov_b32_e32 v33, v50
	v_pk_mul_f32 v[26:27], v[26:27], v[32:33]
	v_pk_mul_f32 v[24:25], v[24:25], v[50:51]
	v_pk_mul_f32 v[26:27], v[30:31], v[26:27]
	v_pk_mul_f32 v[24:25], v[28:29], v[24:25]
	global_store_dwordx4 v[48:49], v[24:27], off nt
	s_nop 1
	v_mov_b64_e32 v[24:25], v[84:85]
	v_mov_b64_e32 v[26:27], v[86:87]
	v_mov_b32_e32 v28, v52
	v_mov_b32_e32 v29, v52
	v_pk_mul_f32 v[18:19], v[18:19], v[28:29]
	v_pk_mul_f32 v[20:21], v[20:21], v[50:51]
	v_pk_mul_f32 v[22:23], v[22:23], v[32:33]
	s_nop 0
	v_pk_mul_f32 v[18:19], v[18:19], v[26:27]
	v_pk_mul_f32 v[16:17], v[16:17], v[24:25]
	v_pk_mul_f32 v[34:35], v[22:23], v[26:27]
	global_store_dwordx4 v[44:45], v[16:19], off offset:1024 nt
	v_pk_mul_f32 v[32:33], v[20:21], v[24:25]
